# PC1 gated epilogue: bf16 unpack into an aligned pair + v_pk_mul_f32 / v_pk_add_f32 (192 sites), same roundings
# speedup vs baseline: 1.0057x; 1.0057x over previous
.Lpc1_fast_b0n:
	v_lshlrev_b64 v[206:207], 1, v[130:131]
	v_lshl_add_u64 v[208:209], s[24:25], 0, v[136:137]
	v_lshl_add_u64 v[208:209], s[54:55], 1, v[208:209]
	v_lshl_add_u64 v[208:209], v[208:209], 0, v[206:207]
	s_and_b64 s[36:37], s[50:51], exec
	s_cselect_b32 s46, s22, s26
	s_cselect_b32 s47, s23, s27
	v_lshl_add_u64 v[212:213], v[134:135], 1, s[46:47]
	v_lshl_add_u64 v[212:213], v[212:213], 0, v[206:207]
	s_mov_b64 s[30:31], 0x18000
	s_mov_b64 s[34:35], 0x78000
	s_mov_b64 s[36:37], 0x8000
	s_mov_b64 s[44:45], 0x28000
	global_load_dwordx4 v[138:141], v[208:209], off
	v_lshl_add_u64 v[208:209], v[208:209], 0, s[30:31]
	global_load_dwordx4 v[142:145], v[208:209], off
	v_lshl_add_u64 v[208:209], v[208:209], 0, s[30:31]
	global_load_dwordx4 v[146:149], v[208:209], off
	v_lshl_add_u64 v[208:209], v[208:209], 0, s[30:31]
	global_load_dwordx4 v[150:153], v[208:209], off
	v_lshl_add_u64 v[208:209], v[208:209], 0, s[34:35]
	global_load_dwordx4 v[154:157], v[208:209], off
	v_lshl_add_u64 v[208:209], v[208:209], 0, s[30:31]
	global_load_dwordx4 v[158:161], v[208:209], off
	v_lshl_add_u64 v[208:209], v[208:209], 0, s[30:31]
	global_load_dwordx4 v[162:165], v[208:209], off
	v_lshl_add_u64 v[208:209], v[208:209], 0, s[30:31]
	global_load_dwordx4 v[166:169], v[208:209], off
	s_waitcnt vmcnt(7)
	v_lshlrev_b32_e32 v218, 16, v138
	v_and_b32_e32 v219, 0xffff0000, v138
	v_pk_mul_f32 v[124:125], v[124:125], v[218:219]
	v_lshlrev_b32_e32 v218, 16, v139
	v_and_b32_e32 v219, 0xffff0000, v139
	v_pk_mul_f32 v[126:127], v[126:127], v[218:219]
	v_lshlrev_b32_e32 v218, 16, v140
	v_and_b32_e32 v219, 0xffff0000, v140
	v_pk_mul_f32 v[120:121], v[120:121], v[218:219]
	v_lshlrev_b32_e32 v218, 16, v141
	v_and_b32_e32 v219, 0xffff0000, v141
	v_pk_mul_f32 v[122:123], v[122:123], v[218:219]
	v_cvt_pk_bf16_f32 v138, v124, v125
	v_cvt_pk_bf16_f32 v139, v126, v127
	v_cvt_pk_bf16_f32 v140, v120, v121
	v_cvt_pk_bf16_f32 v141, v122, v123
	global_store_dwordx4 v[212:213], v[138:141], off
	s_nop 0
	v_lshl_add_u64 v[212:213], v[212:213], 0, s[36:37]
	s_waitcnt vmcnt(7)
	v_lshlrev_b32_e32 v218, 16, v142
	v_and_b32_e32 v219, 0xffff0000, v142
	v_pk_mul_f32 v[108:109], v[108:109], v[218:219]
	v_lshlrev_b32_e32 v218, 16, v143
	v_and_b32_e32 v219, 0xffff0000, v143
	v_pk_mul_f32 v[110:111], v[110:111], v[218:219]
	v_lshlrev_b32_e32 v218, 16, v144
	v_and_b32_e32 v219, 0xffff0000, v144
	v_pk_mul_f32 v[104:105], v[104:105], v[218:219]
	v_lshlrev_b32_e32 v218, 16, v145
	v_and_b32_e32 v219, 0xffff0000, v145
	v_pk_mul_f32 v[106:107], v[106:107], v[218:219]
	v_cvt_pk_bf16_f32 v142, v108, v109
	v_cvt_pk_bf16_f32 v143, v110, v111
	v_cvt_pk_bf16_f32 v144, v104, v105
	v_cvt_pk_bf16_f32 v145, v106, v107
	global_store_dwordx4 v[212:213], v[142:145], off
	s_nop 0
	v_lshl_add_u64 v[212:213], v[212:213], 0, s[36:37]
	s_waitcnt vmcnt(7)
	v_lshlrev_b32_e32 v218, 16, v146
	v_and_b32_e32 v219, 0xffff0000, v146
	v_pk_mul_f32 v[92:93], v[92:93], v[218:219]
	v_lshlrev_b32_e32 v218, 16, v147
	v_and_b32_e32 v219, 0xffff0000, v147
	v_pk_mul_f32 v[94:95], v[94:95], v[218:219]
	v_lshlrev_b32_e32 v218, 16, v148
	v_and_b32_e32 v219, 0xffff0000, v148
	v_pk_mul_f32 v[88:89], v[88:89], v[218:219]
	v_lshlrev_b32_e32 v218, 16, v149
	v_and_b32_e32 v219, 0xffff0000, v149
	v_pk_mul_f32 v[90:91], v[90:91], v[218:219]
	v_cvt_pk_bf16_f32 v146, v92, v93
	v_cvt_pk_bf16_f32 v147, v94, v95
	v_cvt_pk_bf16_f32 v148, v88, v89
	v_cvt_pk_bf16_f32 v149, v90, v91
	global_store_dwordx4 v[212:213], v[146:149], off
	s_nop 0
	v_lshl_add_u64 v[212:213], v[212:213], 0, s[36:37]
	s_waitcnt vmcnt(7)
	v_lshlrev_b32_e32 v218, 16, v150
	v_and_b32_e32 v219, 0xffff0000, v150
	v_pk_mul_f32 v[76:77], v[76:77], v[218:219]
	v_lshlrev_b32_e32 v218, 16, v151
	v_and_b32_e32 v219, 0xffff0000, v151
	v_pk_mul_f32 v[78:79], v[78:79], v[218:219]
	v_lshlrev_b32_e32 v218, 16, v152
	v_and_b32_e32 v219, 0xffff0000, v152
	v_pk_mul_f32 v[72:73], v[72:73], v[218:219]
	v_lshlrev_b32_e32 v218, 16, v153
	v_and_b32_e32 v219, 0xffff0000, v153
	v_pk_mul_f32 v[74:75], v[74:75], v[218:219]
	v_cvt_pk_bf16_f32 v150, v76, v77
	v_cvt_pk_bf16_f32 v151, v78, v79
	v_cvt_pk_bf16_f32 v152, v72, v73
	v_cvt_pk_bf16_f32 v153, v74, v75
	global_store_dwordx4 v[212:213], v[150:153], off
	s_nop 0
	v_lshl_add_u64 v[212:213], v[212:213], 0, s[44:45]
	s_waitcnt vmcnt(7)
	v_lshlrev_b32_e32 v218, 16, v154
	v_and_b32_e32 v219, 0xffff0000, v154
	v_pk_mul_f32 v[60:61], v[60:61], v[218:219]
	v_lshlrev_b32_e32 v218, 16, v155
	v_and_b32_e32 v219, 0xffff0000, v155
	v_pk_mul_f32 v[62:63], v[62:63], v[218:219]
	v_lshlrev_b32_e32 v218, 16, v156
	v_and_b32_e32 v219, 0xffff0000, v156
	v_pk_mul_f32 v[56:57], v[56:57], v[218:219]
	v_lshlrev_b32_e32 v218, 16, v157
	v_and_b32_e32 v219, 0xffff0000, v157
	v_pk_mul_f32 v[58:59], v[58:59], v[218:219]
	v_cvt_pk_bf16_f32 v154, v60, v61
	v_cvt_pk_bf16_f32 v155, v62, v63
	v_cvt_pk_bf16_f32 v156, v56, v57
	v_cvt_pk_bf16_f32 v157, v58, v59
	global_store_dwordx4 v[212:213], v[154:157], off
	s_nop 0
	v_lshl_add_u64 v[212:213], v[212:213], 0, s[36:37]
	s_waitcnt vmcnt(7)
	v_lshlrev_b32_e32 v218, 16, v158
	v_and_b32_e32 v219, 0xffff0000, v158
	v_pk_mul_f32 v[44:45], v[44:45], v[218:219]
	v_lshlrev_b32_e32 v218, 16, v159
	v_and_b32_e32 v219, 0xffff0000, v159
	v_pk_mul_f32 v[46:47], v[46:47], v[218:219]
	v_lshlrev_b32_e32 v218, 16, v160
	v_and_b32_e32 v219, 0xffff0000, v160
	v_pk_mul_f32 v[40:41], v[40:41], v[218:219]
	v_lshlrev_b32_e32 v218, 16, v161
	v_and_b32_e32 v219, 0xffff0000, v161
	v_pk_mul_f32 v[42:43], v[42:43], v[218:219]
	v_cvt_pk_bf16_f32 v158, v44, v45
	v_cvt_pk_bf16_f32 v159, v46, v47
	v_cvt_pk_bf16_f32 v160, v40, v41
	v_cvt_pk_bf16_f32 v161, v42, v43
	global_store_dwordx4 v[212:213], v[158:161], off
	s_nop 0
	v_lshl_add_u64 v[212:213], v[212:213], 0, s[36:37]
	s_waitcnt vmcnt(7)
	v_lshlrev_b32_e32 v218, 16, v162
	v_and_b32_e32 v219, 0xffff0000, v162
	v_pk_mul_f32 v[28:29], v[28:29], v[218:219]
	v_lshlrev_b32_e32 v218, 16, v163
	v_and_b32_e32 v219, 0xffff0000, v163
	v_pk_mul_f32 v[30:31], v[30:31], v[218:219]
	v_lshlrev_b32_e32 v218, 16, v164
	v_and_b32_e32 v219, 0xffff0000, v164
	v_pk_mul_f32 v[24:25], v[24:25], v[218:219]
	v_lshlrev_b32_e32 v218, 16, v165
	v_and_b32_e32 v219, 0xffff0000, v165
	v_pk_mul_f32 v[26:27], v[26:27], v[218:219]
	v_cvt_pk_bf16_f32 v162, v28, v29
	v_cvt_pk_bf16_f32 v163, v30, v31
	v_cvt_pk_bf16_f32 v164, v24, v25
	v_cvt_pk_bf16_f32 v165, v26, v27
	global_store_dwordx4 v[212:213], v[162:165], off
	s_nop 0
	v_lshl_add_u64 v[212:213], v[212:213], 0, s[36:37]
	s_waitcnt vmcnt(7)
	v_lshlrev_b32_e32 v218, 16, v166
	v_and_b32_e32 v219, 0xffff0000, v166
	v_pk_mul_f32 v[12:13], v[12:13], v[218:219]
	v_lshlrev_b32_e32 v218, 16, v167
	v_and_b32_e32 v219, 0xffff0000, v167
	v_pk_mul_f32 v[14:15], v[14:15], v[218:219]
	v_lshlrev_b32_e32 v218, 16, v168
	v_and_b32_e32 v219, 0xffff0000, v168
	v_pk_mul_f32 v[8:9], v[8:9], v[218:219]
	v_lshlrev_b32_e32 v218, 16, v169
	v_and_b32_e32 v219, 0xffff0000, v169
	v_pk_mul_f32 v[10:11], v[10:11], v[218:219]
	v_cvt_pk_bf16_f32 v166, v12, v13
	v_cvt_pk_bf16_f32 v167, v14, v15
	v_cvt_pk_bf16_f32 v168, v8, v9
	v_cvt_pk_bf16_f32 v169, v10, v11
	global_store_dwordx4 v[212:213], v[166:169], off
	s_branch .LBB0_1411
.Lpc1_fast_b0t:
	v_lshlrev_b64 v[206:207], 1, v[130:131]
	v_lshl_add_u64 v[208:209], s[24:25], 0, v[136:137]
	v_lshl_add_u64 v[208:209], s[54:55], 1, v[208:209]
	v_lshl_add_u64 v[208:209], v[208:209], 0, v[206:207]
	v_lshl_add_u64 v[210:211], v[134:135], 1, s[22:23]
	v_lshl_add_u64 v[210:211], v[210:211], 0, v[206:207]
	s_and_b64 s[36:37], s[50:51], exec
	s_cselect_b32 s46, s22, s26
	s_cselect_b32 s47, s23, s27
	v_lshl_add_u64 v[212:213], v[134:135], 1, s[46:47]
	v_lshl_add_u64 v[212:213], v[212:213], 0, v[206:207]
	s_mov_b64 s[30:31], 0x18000
	s_mov_b64 s[34:35], 0x78000
	s_mov_b64 s[36:37], 0x8000
	s_mov_b64 s[44:45], 0x28000
	global_load_dwordx4 v[138:141], v[208:209], off
	global_load_dwordx4 v[170:173], v[210:211], off
	v_lshl_add_u64 v[208:209], v[208:209], 0, s[30:31]
	v_lshl_add_u64 v[210:211], v[210:211], 0, s[36:37]
	global_load_dwordx4 v[142:145], v[208:209], off
	global_load_dwordx4 v[174:177], v[210:211], off
	v_lshl_add_u64 v[208:209], v[208:209], 0, s[30:31]
	v_lshl_add_u64 v[210:211], v[210:211], 0, s[36:37]
	global_load_dwordx4 v[146:149], v[208:209], off
	global_load_dwordx4 v[178:181], v[210:211], off
	v_lshl_add_u64 v[208:209], v[208:209], 0, s[30:31]
	v_lshl_add_u64 v[210:211], v[210:211], 0, s[36:37]
	global_load_dwordx4 v[150:153], v[208:209], off
	global_load_dwordx4 v[182:185], v[210:211], off
	v_lshl_add_u64 v[208:209], v[208:209], 0, s[34:35]
	v_lshl_add_u64 v[210:211], v[210:211], 0, s[44:45]
	global_load_dwordx4 v[154:157], v[208:209], off
	global_load_dwordx4 v[186:189], v[210:211], off
	v_lshl_add_u64 v[208:209], v[208:209], 0, s[30:31]
	v_lshl_add_u64 v[210:211], v[210:211], 0, s[36:37]
	global_load_dwordx4 v[158:161], v[208:209], off
	global_load_dwordx4 v[190:193], v[210:211], off
	v_lshl_add_u64 v[208:209], v[208:209], 0, s[30:31]
	v_lshl_add_u64 v[210:211], v[210:211], 0, s[36:37]
	global_load_dwordx4 v[162:165], v[208:209], off
	global_load_dwordx4 v[130:133], v[210:211], off
	v_lshl_add_u64 v[208:209], v[208:209], 0, s[30:31]
	v_lshl_add_u64 v[210:211], v[210:211], 0, s[36:37]
	global_load_dwordx4 v[166:169], v[208:209], off
	global_load_dwordx4 v[134:137], v[210:211], off
	s_waitcnt vmcnt(14)
	v_lshlrev_b32_e32 v218, 16, v138
	v_and_b32_e32 v219, 0xffff0000, v138
	v_pk_mul_f32 v[124:125], v[124:125], v[218:219]
	v_lshlrev_b32_e32 v218, 16, v139
	v_and_b32_e32 v219, 0xffff0000, v139
	v_pk_mul_f32 v[126:127], v[126:127], v[218:219]
	v_lshlrev_b32_e32 v218, 16, v140
	v_and_b32_e32 v219, 0xffff0000, v140
	v_pk_mul_f32 v[120:121], v[120:121], v[218:219]
	v_lshlrev_b32_e32 v218, 16, v141
	v_and_b32_e32 v219, 0xffff0000, v141
	v_pk_mul_f32 v[122:123], v[122:123], v[218:219]
	v_lshlrev_b32_e32 v218, 16, v170
	v_and_b32_e32 v219, 0xffff0000, v170
	v_pk_add_f32 v[124:125], v[124:125], v[218:219]
	v_lshlrev_b32_e32 v218, 16, v171
	v_and_b32_e32 v219, 0xffff0000, v171
	v_pk_add_f32 v[126:127], v[126:127], v[218:219]
	v_lshlrev_b32_e32 v218, 16, v172
	v_and_b32_e32 v219, 0xffff0000, v172
	v_pk_add_f32 v[120:121], v[120:121], v[218:219]
	v_lshlrev_b32_e32 v218, 16, v173
	v_and_b32_e32 v219, 0xffff0000, v173
	v_pk_add_f32 v[122:123], v[122:123], v[218:219]
	v_cvt_pk_bf16_f32 v138, v124, v125
	v_cvt_pk_bf16_f32 v139, v126, v127
	v_cvt_pk_bf16_f32 v140, v120, v121
	v_cvt_pk_bf16_f32 v141, v122, v123
	global_store_dwordx4 v[212:213], v[138:141], off
	s_nop 0
	v_lshl_add_u64 v[212:213], v[212:213], 0, s[36:37]
	s_waitcnt vmcnt(13)
	v_lshlrev_b32_e32 v218, 16, v142
	v_and_b32_e32 v219, 0xffff0000, v142
	v_pk_mul_f32 v[108:109], v[108:109], v[218:219]
	v_lshlrev_b32_e32 v218, 16, v143
	v_and_b32_e32 v219, 0xffff0000, v143
	v_pk_mul_f32 v[110:111], v[110:111], v[218:219]
	v_lshlrev_b32_e32 v218, 16, v144
	v_and_b32_e32 v219, 0xffff0000, v144
	v_pk_mul_f32 v[104:105], v[104:105], v[218:219]
	v_lshlrev_b32_e32 v218, 16, v145
	v_and_b32_e32 v219, 0xffff0000, v145
	v_pk_mul_f32 v[106:107], v[106:107], v[218:219]
	v_lshlrev_b32_e32 v218, 16, v174
	v_and_b32_e32 v219, 0xffff0000, v174
	v_pk_add_f32 v[108:109], v[108:109], v[218:219]
	v_lshlrev_b32_e32 v218, 16, v175
	v_and_b32_e32 v219, 0xffff0000, v175
	v_pk_add_f32 v[110:111], v[110:111], v[218:219]
	v_lshlrev_b32_e32 v218, 16, v176
	v_and_b32_e32 v219, 0xffff0000, v176
	v_pk_add_f32 v[104:105], v[104:105], v[218:219]
	v_lshlrev_b32_e32 v218, 16, v177
	v_and_b32_e32 v219, 0xffff0000, v177
	v_pk_add_f32 v[106:107], v[106:107], v[218:219]
	v_cvt_pk_bf16_f32 v142, v108, v109
	v_cvt_pk_bf16_f32 v143, v110, v111
	v_cvt_pk_bf16_f32 v144, v104, v105
	v_cvt_pk_bf16_f32 v145, v106, v107
	global_store_dwordx4 v[212:213], v[142:145], off
	s_nop 0
	v_lshl_add_u64 v[212:213], v[212:213], 0, s[36:37]
	s_waitcnt vmcnt(12)
	v_lshlrev_b32_e32 v218, 16, v146
	v_and_b32_e32 v219, 0xffff0000, v146
	v_pk_mul_f32 v[92:93], v[92:93], v[218:219]
	v_lshlrev_b32_e32 v218, 16, v147
	v_and_b32_e32 v219, 0xffff0000, v147
	v_pk_mul_f32 v[94:95], v[94:95], v[218:219]
	v_lshlrev_b32_e32 v218, 16, v148
	v_and_b32_e32 v219, 0xffff0000, v148
	v_pk_mul_f32 v[88:89], v[88:89], v[218:219]
	v_lshlrev_b32_e32 v218, 16, v149
	v_and_b32_e32 v219, 0xffff0000, v149
	v_pk_mul_f32 v[90:91], v[90:91], v[218:219]
	v_lshlrev_b32_e32 v218, 16, v178
	v_and_b32_e32 v219, 0xffff0000, v178
	v_pk_add_f32 v[92:93], v[92:93], v[218:219]
	v_lshlrev_b32_e32 v218, 16, v179
	v_and_b32_e32 v219, 0xffff0000, v179
	v_pk_add_f32 v[94:95], v[94:95], v[218:219]
	v_lshlrev_b32_e32 v218, 16, v180
	v_and_b32_e32 v219, 0xffff0000, v180
	v_pk_add_f32 v[88:89], v[88:89], v[218:219]
	v_lshlrev_b32_e32 v218, 16, v181
	v_and_b32_e32 v219, 0xffff0000, v181
	v_pk_add_f32 v[90:91], v[90:91], v[218:219]
	v_cvt_pk_bf16_f32 v146, v92, v93
	v_cvt_pk_bf16_f32 v147, v94, v95
	v_cvt_pk_bf16_f32 v148, v88, v89
	v_cvt_pk_bf16_f32 v149, v90, v91
	global_store_dwordx4 v[212:213], v[146:149], off
	s_nop 0
	v_lshl_add_u64 v[212:213], v[212:213], 0, s[36:37]
	s_waitcnt vmcnt(11)
	v_lshlrev_b32_e32 v218, 16, v150
	v_and_b32_e32 v219, 0xffff0000, v150
	v_pk_mul_f32 v[76:77], v[76:77], v[218:219]
	v_lshlrev_b32_e32 v218, 16, v151
	v_and_b32_e32 v219, 0xffff0000, v151
	v_pk_mul_f32 v[78:79], v[78:79], v[218:219]
	v_lshlrev_b32_e32 v218, 16, v152
	v_and_b32_e32 v219, 0xffff0000, v152
	v_pk_mul_f32 v[72:73], v[72:73], v[218:219]
	v_lshlrev_b32_e32 v218, 16, v153
	v_and_b32_e32 v219, 0xffff0000, v153
	v_pk_mul_f32 v[74:75], v[74:75], v[218:219]
	v_lshlrev_b32_e32 v218, 16, v182
	v_and_b32_e32 v219, 0xffff0000, v182
	v_pk_add_f32 v[76:77], v[76:77], v[218:219]
	v_lshlrev_b32_e32 v218, 16, v183
	v_and_b32_e32 v219, 0xffff0000, v183
	v_pk_add_f32 v[78:79], v[78:79], v[218:219]
	v_lshlrev_b32_e32 v218, 16, v184
	v_and_b32_e32 v219, 0xffff0000, v184
	v_pk_add_f32 v[72:73], v[72:73], v[218:219]
	v_lshlrev_b32_e32 v218, 16, v185
	v_and_b32_e32 v219, 0xffff0000, v185
	v_pk_add_f32 v[74:75], v[74:75], v[218:219]
	v_cvt_pk_bf16_f32 v150, v76, v77
	v_cvt_pk_bf16_f32 v151, v78, v79
	v_cvt_pk_bf16_f32 v152, v72, v73
	v_cvt_pk_bf16_f32 v153, v74, v75
	global_store_dwordx4 v[212:213], v[150:153], off
	s_nop 0
	v_lshl_add_u64 v[212:213], v[212:213], 0, s[44:45]
	s_waitcnt vmcnt(10)
	v_lshlrev_b32_e32 v218, 16, v154
	v_and_b32_e32 v219, 0xffff0000, v154
	v_pk_mul_f32 v[60:61], v[60:61], v[218:219]
	v_lshlrev_b32_e32 v218, 16, v155
	v_and_b32_e32 v219, 0xffff0000, v155
	v_pk_mul_f32 v[62:63], v[62:63], v[218:219]
	v_lshlrev_b32_e32 v218, 16, v156
	v_and_b32_e32 v219, 0xffff0000, v156
	v_pk_mul_f32 v[56:57], v[56:57], v[218:219]
	v_lshlrev_b32_e32 v218, 16, v157
	v_and_b32_e32 v219, 0xffff0000, v157
	v_pk_mul_f32 v[58:59], v[58:59], v[218:219]
	v_lshlrev_b32_e32 v218, 16, v186
	v_and_b32_e32 v219, 0xffff0000, v186
	v_pk_add_f32 v[60:61], v[60:61], v[218:219]
	v_lshlrev_b32_e32 v218, 16, v187
	v_and_b32_e32 v219, 0xffff0000, v187
	v_pk_add_f32 v[62:63], v[62:63], v[218:219]
	v_lshlrev_b32_e32 v218, 16, v188
	v_and_b32_e32 v219, 0xffff0000, v188
	v_pk_add_f32 v[56:57], v[56:57], v[218:219]
	v_lshlrev_b32_e32 v218, 16, v189
	v_and_b32_e32 v219, 0xffff0000, v189
	v_pk_add_f32 v[58:59], v[58:59], v[218:219]
	v_cvt_pk_bf16_f32 v154, v60, v61
	v_cvt_pk_bf16_f32 v155, v62, v63
	v_cvt_pk_bf16_f32 v156, v56, v57
	v_cvt_pk_bf16_f32 v157, v58, v59
	global_store_dwordx4 v[212:213], v[154:157], off
	s_nop 0
	v_lshl_add_u64 v[212:213], v[212:213], 0, s[36:37]
	s_waitcnt vmcnt(9)
	v_lshlrev_b32_e32 v218, 16, v158
	v_and_b32_e32 v219, 0xffff0000, v158
	v_pk_mul_f32 v[44:45], v[44:45], v[218:219]
	v_lshlrev_b32_e32 v218, 16, v159
	v_and_b32_e32 v219, 0xffff0000, v159
	v_pk_mul_f32 v[46:47], v[46:47], v[218:219]
	v_lshlrev_b32_e32 v218, 16, v160
	v_and_b32_e32 v219, 0xffff0000, v160
	v_pk_mul_f32 v[40:41], v[40:41], v[218:219]
	v_lshlrev_b32_e32 v218, 16, v161
	v_and_b32_e32 v219, 0xffff0000, v161
	v_pk_mul_f32 v[42:43], v[42:43], v[218:219]
	v_lshlrev_b32_e32 v218, 16, v190
	v_and_b32_e32 v219, 0xffff0000, v190
	v_pk_add_f32 v[44:45], v[44:45], v[218:219]
	v_lshlrev_b32_e32 v218, 16, v191
	v_and_b32_e32 v219, 0xffff0000, v191
	v_pk_add_f32 v[46:47], v[46:47], v[218:219]
	v_lshlrev_b32_e32 v218, 16, v192
	v_and_b32_e32 v219, 0xffff0000, v192
	v_pk_add_f32 v[40:41], v[40:41], v[218:219]
	v_lshlrev_b32_e32 v218, 16, v193
	v_and_b32_e32 v219, 0xffff0000, v193
	v_pk_add_f32 v[42:43], v[42:43], v[218:219]
	v_cvt_pk_bf16_f32 v158, v44, v45
	v_cvt_pk_bf16_f32 v159, v46, v47
	v_cvt_pk_bf16_f32 v160, v40, v41
	v_cvt_pk_bf16_f32 v161, v42, v43
	global_store_dwordx4 v[212:213], v[158:161], off
	s_nop 0
	v_lshl_add_u64 v[212:213], v[212:213], 0, s[36:37]
	s_waitcnt vmcnt(8)
	v_lshlrev_b32_e32 v218, 16, v162
	v_and_b32_e32 v219, 0xffff0000, v162
	v_pk_mul_f32 v[28:29], v[28:29], v[218:219]
	v_lshlrev_b32_e32 v218, 16, v163
	v_and_b32_e32 v219, 0xffff0000, v163
	v_pk_mul_f32 v[30:31], v[30:31], v[218:219]
	v_lshlrev_b32_e32 v218, 16, v164
	v_and_b32_e32 v219, 0xffff0000, v164
	v_pk_mul_f32 v[24:25], v[24:25], v[218:219]
	v_lshlrev_b32_e32 v218, 16, v165
	v_and_b32_e32 v219, 0xffff0000, v165
	v_pk_mul_f32 v[26:27], v[26:27], v[218:219]
	v_lshlrev_b32_e32 v218, 16, v130
	v_and_b32_e32 v219, 0xffff0000, v130
	v_pk_add_f32 v[28:29], v[28:29], v[218:219]
	v_lshlrev_b32_e32 v218, 16, v131
	v_and_b32_e32 v219, 0xffff0000, v131
	v_pk_add_f32 v[30:31], v[30:31], v[218:219]
	v_lshlrev_b32_e32 v218, 16, v132
	v_and_b32_e32 v219, 0xffff0000, v132
	v_pk_add_f32 v[24:25], v[24:25], v[218:219]
	v_lshlrev_b32_e32 v218, 16, v133
	v_and_b32_e32 v219, 0xffff0000, v133
	v_pk_add_f32 v[26:27], v[26:27], v[218:219]
	v_cvt_pk_bf16_f32 v162, v28, v29
	v_cvt_pk_bf16_f32 v163, v30, v31
	v_cvt_pk_bf16_f32 v164, v24, v25
	v_cvt_pk_bf16_f32 v165, v26, v27
	global_store_dwordx4 v[212:213], v[162:165], off
	s_nop 0
	v_lshl_add_u64 v[212:213], v[212:213], 0, s[36:37]
	s_waitcnt vmcnt(7)
	v_lshlrev_b32_e32 v218, 16, v166
	v_and_b32_e32 v219, 0xffff0000, v166
	v_pk_mul_f32 v[12:13], v[12:13], v[218:219]
	v_lshlrev_b32_e32 v218, 16, v167
	v_and_b32_e32 v219, 0xffff0000, v167
	v_pk_mul_f32 v[14:15], v[14:15], v[218:219]
	v_lshlrev_b32_e32 v218, 16, v168
	v_and_b32_e32 v219, 0xffff0000, v168
	v_pk_mul_f32 v[8:9], v[8:9], v[218:219]
	v_lshlrev_b32_e32 v218, 16, v169
	v_and_b32_e32 v219, 0xffff0000, v169
	v_pk_mul_f32 v[10:11], v[10:11], v[218:219]
	v_lshlrev_b32_e32 v218, 16, v134
	v_and_b32_e32 v219, 0xffff0000, v134
	v_pk_add_f32 v[12:13], v[12:13], v[218:219]
	v_lshlrev_b32_e32 v218, 16, v135
	v_and_b32_e32 v219, 0xffff0000, v135
	v_pk_add_f32 v[14:15], v[14:15], v[218:219]
	v_lshlrev_b32_e32 v218, 16, v136
	v_and_b32_e32 v219, 0xffff0000, v136
	v_pk_add_f32 v[8:9], v[8:9], v[218:219]
	v_lshlrev_b32_e32 v218, 16, v137
	v_and_b32_e32 v219, 0xffff0000, v137
	v_pk_add_f32 v[10:11], v[10:11], v[218:219]
	v_cvt_pk_bf16_f32 v166, v12, v13
	v_cvt_pk_bf16_f32 v167, v14, v15
	v_cvt_pk_bf16_f32 v168, v8, v9
	v_cvt_pk_bf16_f32 v169, v10, v11
	global_store_dwordx4 v[212:213], v[166:169], off
	s_branch .LBB0_1411

.Lpc1_fast_b1n:
	v_lshlrev_b64 v[206:207], 1, v[130:131]
	v_lshl_add_u64 v[208:209], s[24:25], 0, v[136:137]
	v_lshl_add_u64 v[208:209], s[54:55], 1, v[208:209]
	v_lshl_add_u64 v[208:209], v[208:209], 0, v[206:207]
	s_and_b64 s[36:37], s[50:51], exec
	s_cselect_b32 s46, s22, s26
	s_cselect_b32 s47, s23, s27
	v_lshl_add_u64 v[212:213], v[134:135], 1, s[46:47]
	v_lshl_add_u64 v[212:213], v[212:213], 0, v[206:207]
	s_mov_b64 s[30:31], 0x18000
	s_mov_b64 s[34:35], 0x78000
	s_mov_b64 s[36:37], 0x8000
	s_mov_b64 s[44:45], 0x28000
	global_load_dwordx4 v[138:141], v[208:209], off offset:256
	v_lshl_add_u64 v[208:209], v[208:209], 0, s[30:31]
	global_load_dwordx4 v[142:145], v[208:209], off offset:256
	v_lshl_add_u64 v[208:209], v[208:209], 0, s[30:31]
	global_load_dwordx4 v[146:149], v[208:209], off offset:256
	v_lshl_add_u64 v[208:209], v[208:209], 0, s[30:31]
	global_load_dwordx4 v[150:153], v[208:209], off offset:256
	v_lshl_add_u64 v[208:209], v[208:209], 0, s[34:35]
	global_load_dwordx4 v[154:157], v[208:209], off offset:256
	v_lshl_add_u64 v[208:209], v[208:209], 0, s[30:31]
	global_load_dwordx4 v[158:161], v[208:209], off offset:256
	v_lshl_add_u64 v[208:209], v[208:209], 0, s[30:31]
	global_load_dwordx4 v[162:165], v[208:209], off offset:256
	v_lshl_add_u64 v[208:209], v[208:209], 0, s[30:31]
	global_load_dwordx4 v[166:169], v[208:209], off offset:256
	s_waitcnt vmcnt(7)
	v_lshlrev_b32_e32 v218, 16, v138
	v_and_b32_e32 v219, 0xffff0000, v138
	v_pk_mul_f32 v[116:117], v[116:117], v[218:219]
	v_lshlrev_b32_e32 v218, 16, v139
	v_and_b32_e32 v219, 0xffff0000, v139
	v_pk_mul_f32 v[118:119], v[118:119], v[218:219]
	v_lshlrev_b32_e32 v218, 16, v140
	v_and_b32_e32 v219, 0xffff0000, v140
	v_pk_mul_f32 v[112:113], v[112:113], v[218:219]
	v_lshlrev_b32_e32 v218, 16, v141
	v_and_b32_e32 v219, 0xffff0000, v141
	v_pk_mul_f32 v[114:115], v[114:115], v[218:219]
	v_cvt_pk_bf16_f32 v138, v116, v117
	v_cvt_pk_bf16_f32 v139, v118, v119
	v_cvt_pk_bf16_f32 v140, v112, v113
	v_cvt_pk_bf16_f32 v141, v114, v115
	global_store_dwordx4 v[212:213], v[138:141], off offset:256
	s_nop 0
	v_lshl_add_u64 v[212:213], v[212:213], 0, s[36:37]
	s_waitcnt vmcnt(7)
	v_lshlrev_b32_e32 v218, 16, v142
	v_and_b32_e32 v219, 0xffff0000, v142
	v_pk_mul_f32 v[100:101], v[100:101], v[218:219]
	v_lshlrev_b32_e32 v218, 16, v143
	v_and_b32_e32 v219, 0xffff0000, v143
	v_pk_mul_f32 v[102:103], v[102:103], v[218:219]
	v_lshlrev_b32_e32 v218, 16, v144
	v_and_b32_e32 v219, 0xffff0000, v144
	v_pk_mul_f32 v[96:97], v[96:97], v[218:219]
	v_lshlrev_b32_e32 v218, 16, v145
	v_and_b32_e32 v219, 0xffff0000, v145
	v_pk_mul_f32 v[98:99], v[98:99], v[218:219]
	v_cvt_pk_bf16_f32 v142, v100, v101
	v_cvt_pk_bf16_f32 v143, v102, v103
	v_cvt_pk_bf16_f32 v144, v96, v97
	v_cvt_pk_bf16_f32 v145, v98, v99
	global_store_dwordx4 v[212:213], v[142:145], off offset:256
	s_nop 0
	v_lshl_add_u64 v[212:213], v[212:213], 0, s[36:37]
	s_waitcnt vmcnt(7)
	v_lshlrev_b32_e32 v218, 16, v146
	v_and_b32_e32 v219, 0xffff0000, v146
	v_pk_mul_f32 v[84:85], v[84:85], v[218:219]
	v_lshlrev_b32_e32 v218, 16, v147
	v_and_b32_e32 v219, 0xffff0000, v147
	v_pk_mul_f32 v[86:87], v[86:87], v[218:219]
	v_lshlrev_b32_e32 v218, 16, v148
	v_and_b32_e32 v219, 0xffff0000, v148
	v_pk_mul_f32 v[80:81], v[80:81], v[218:219]
	v_lshlrev_b32_e32 v218, 16, v149
	v_and_b32_e32 v219, 0xffff0000, v149
	v_pk_mul_f32 v[82:83], v[82:83], v[218:219]
	v_cvt_pk_bf16_f32 v146, v84, v85
	v_cvt_pk_bf16_f32 v147, v86, v87
	v_cvt_pk_bf16_f32 v148, v80, v81
	v_cvt_pk_bf16_f32 v149, v82, v83
	global_store_dwordx4 v[212:213], v[146:149], off offset:256
	s_nop 0
	v_lshl_add_u64 v[212:213], v[212:213], 0, s[36:37]
	s_waitcnt vmcnt(7)
	v_lshlrev_b32_e32 v218, 16, v150
	v_and_b32_e32 v219, 0xffff0000, v150
	v_pk_mul_f32 v[68:69], v[68:69], v[218:219]
	v_lshlrev_b32_e32 v218, 16, v151
	v_and_b32_e32 v219, 0xffff0000, v151
	v_pk_mul_f32 v[70:71], v[70:71], v[218:219]
	v_lshlrev_b32_e32 v218, 16, v152
	v_and_b32_e32 v219, 0xffff0000, v152
	v_pk_mul_f32 v[64:65], v[64:65], v[218:219]
	v_lshlrev_b32_e32 v218, 16, v153
	v_and_b32_e32 v219, 0xffff0000, v153
	v_pk_mul_f32 v[66:67], v[66:67], v[218:219]
	v_cvt_pk_bf16_f32 v150, v68, v69
	v_cvt_pk_bf16_f32 v151, v70, v71
	v_cvt_pk_bf16_f32 v152, v64, v65
	v_cvt_pk_bf16_f32 v153, v66, v67
	global_store_dwordx4 v[212:213], v[150:153], off offset:256
	s_nop 0
	v_lshl_add_u64 v[212:213], v[212:213], 0, s[44:45]
	s_waitcnt vmcnt(7)
	v_lshlrev_b32_e32 v218, 16, v154
	v_and_b32_e32 v219, 0xffff0000, v154
	v_pk_mul_f32 v[52:53], v[52:53], v[218:219]
	v_lshlrev_b32_e32 v218, 16, v155
	v_and_b32_e32 v219, 0xffff0000, v155
	v_pk_mul_f32 v[54:55], v[54:55], v[218:219]
	v_lshlrev_b32_e32 v218, 16, v156
	v_and_b32_e32 v219, 0xffff0000, v156
	v_pk_mul_f32 v[48:49], v[48:49], v[218:219]
	v_lshlrev_b32_e32 v218, 16, v157
	v_and_b32_e32 v219, 0xffff0000, v157
	v_pk_mul_f32 v[50:51], v[50:51], v[218:219]
	v_cvt_pk_bf16_f32 v154, v52, v53
	v_cvt_pk_bf16_f32 v155, v54, v55
	v_cvt_pk_bf16_f32 v156, v48, v49
	v_cvt_pk_bf16_f32 v157, v50, v51
	global_store_dwordx4 v[212:213], v[154:157], off offset:256
	s_nop 0
	v_lshl_add_u64 v[212:213], v[212:213], 0, s[36:37]
	s_waitcnt vmcnt(7)
	v_lshlrev_b32_e32 v218, 16, v158
	v_and_b32_e32 v219, 0xffff0000, v158
	v_pk_mul_f32 v[36:37], v[36:37], v[218:219]
	v_lshlrev_b32_e32 v218, 16, v159
	v_and_b32_e32 v219, 0xffff0000, v159
	v_pk_mul_f32 v[38:39], v[38:39], v[218:219]
	v_lshlrev_b32_e32 v218, 16, v160
	v_and_b32_e32 v219, 0xffff0000, v160
	v_pk_mul_f32 v[32:33], v[32:33], v[218:219]
	v_lshlrev_b32_e32 v218, 16, v161
	v_and_b32_e32 v219, 0xffff0000, v161
	v_pk_mul_f32 v[34:35], v[34:35], v[218:219]
	v_cvt_pk_bf16_f32 v158, v36, v37
	v_cvt_pk_bf16_f32 v159, v38, v39
	v_cvt_pk_bf16_f32 v160, v32, v33
	v_cvt_pk_bf16_f32 v161, v34, v35
	global_store_dwordx4 v[212:213], v[158:161], off offset:256
	s_nop 0
	v_lshl_add_u64 v[212:213], v[212:213], 0, s[36:37]
	s_waitcnt vmcnt(7)
	v_lshlrev_b32_e32 v218, 16, v162
	v_and_b32_e32 v219, 0xffff0000, v162
	v_pk_mul_f32 v[20:21], v[20:21], v[218:219]
	v_lshlrev_b32_e32 v218, 16, v163
	v_and_b32_e32 v219, 0xffff0000, v163
	v_pk_mul_f32 v[22:23], v[22:23], v[218:219]
	v_lshlrev_b32_e32 v218, 16, v164
	v_and_b32_e32 v219, 0xffff0000, v164
	v_pk_mul_f32 v[16:17], v[16:17], v[218:219]
	v_lshlrev_b32_e32 v218, 16, v165
	v_and_b32_e32 v219, 0xffff0000, v165
	v_pk_mul_f32 v[18:19], v[18:19], v[218:219]
	v_cvt_pk_bf16_f32 v162, v20, v21
	v_cvt_pk_bf16_f32 v163, v22, v23
	v_cvt_pk_bf16_f32 v164, v16, v17
	v_cvt_pk_bf16_f32 v165, v18, v19
	global_store_dwordx4 v[212:213], v[162:165], off offset:256
	s_nop 0
	v_lshl_add_u64 v[212:213], v[212:213], 0, s[36:37]
	s_waitcnt vmcnt(7)
	v_lshlrev_b32_e32 v218, 16, v166
	v_and_b32_e32 v219, 0xffff0000, v166
	v_pk_mul_f32 v[4:5], v[4:5], v[218:219]
	v_lshlrev_b32_e32 v218, 16, v167
	v_and_b32_e32 v219, 0xffff0000, v167
	v_pk_mul_f32 v[6:7], v[6:7], v[218:219]
	v_lshlrev_b32_e32 v218, 16, v168
	v_and_b32_e32 v219, 0xffff0000, v168
	v_pk_mul_f32 v[0:1], v[0:1], v[218:219]
	v_lshlrev_b32_e32 v218, 16, v169
	v_and_b32_e32 v219, 0xffff0000, v169
	v_pk_mul_f32 v[2:3], v[2:3], v[218:219]
	v_cvt_pk_bf16_f32 v166, v4, v5
	v_cvt_pk_bf16_f32 v167, v6, v7
	v_cvt_pk_bf16_f32 v168, v0, v1
	v_cvt_pk_bf16_f32 v169, v2, v3
	global_store_dwordx4 v[212:213], v[166:169], off offset:256
	s_branch .LBB0_1411
.Lpc1_fast_b1t:
	v_lshlrev_b64 v[206:207], 1, v[130:131]
	v_lshl_add_u64 v[208:209], s[24:25], 0, v[136:137]
	v_lshl_add_u64 v[208:209], s[54:55], 1, v[208:209]
	v_lshl_add_u64 v[208:209], v[208:209], 0, v[206:207]
	v_lshl_add_u64 v[210:211], v[134:135], 1, s[22:23]
	v_lshl_add_u64 v[210:211], v[210:211], 0, v[206:207]
	s_and_b64 s[36:37], s[50:51], exec
	s_cselect_b32 s46, s22, s26
	s_cselect_b32 s47, s23, s27
	v_lshl_add_u64 v[212:213], v[134:135], 1, s[46:47]
	v_lshl_add_u64 v[212:213], v[212:213], 0, v[206:207]
	s_mov_b64 s[30:31], 0x18000
	s_mov_b64 s[34:35], 0x78000
	s_mov_b64 s[36:37], 0x8000
	s_mov_b64 s[44:45], 0x28000
	global_load_dwordx4 v[138:141], v[208:209], off offset:256
	global_load_dwordx4 v[170:173], v[210:211], off offset:256
	v_lshl_add_u64 v[208:209], v[208:209], 0, s[30:31]
	v_lshl_add_u64 v[210:211], v[210:211], 0, s[36:37]
	global_load_dwordx4 v[142:145], v[208:209], off offset:256
	global_load_dwordx4 v[174:177], v[210:211], off offset:256
	v_lshl_add_u64 v[208:209], v[208:209], 0, s[30:31]
	v_lshl_add_u64 v[210:211], v[210:211], 0, s[36:37]
	global_load_dwordx4 v[146:149], v[208:209], off offset:256
	global_load_dwordx4 v[178:181], v[210:211], off offset:256
	v_lshl_add_u64 v[208:209], v[208:209], 0, s[30:31]
	v_lshl_add_u64 v[210:211], v[210:211], 0, s[36:37]
	global_load_dwordx4 v[150:153], v[208:209], off offset:256
	global_load_dwordx4 v[182:185], v[210:211], off offset:256
	v_lshl_add_u64 v[208:209], v[208:209], 0, s[34:35]
	v_lshl_add_u64 v[210:211], v[210:211], 0, s[44:45]
	global_load_dwordx4 v[154:157], v[208:209], off offset:256
	global_load_dwordx4 v[186:189], v[210:211], off offset:256
	v_lshl_add_u64 v[208:209], v[208:209], 0, s[30:31]
	v_lshl_add_u64 v[210:211], v[210:211], 0, s[36:37]
	global_load_dwordx4 v[158:161], v[208:209], off offset:256
	global_load_dwordx4 v[190:193], v[210:211], off offset:256
	v_lshl_add_u64 v[208:209], v[208:209], 0, s[30:31]
	v_lshl_add_u64 v[210:211], v[210:211], 0, s[36:37]
	global_load_dwordx4 v[162:165], v[208:209], off offset:256
	global_load_dwordx4 v[130:133], v[210:211], off offset:256
	v_lshl_add_u64 v[208:209], v[208:209], 0, s[30:31]
	v_lshl_add_u64 v[210:211], v[210:211], 0, s[36:37]
	global_load_dwordx4 v[166:169], v[208:209], off offset:256
	global_load_dwordx4 v[134:137], v[210:211], off offset:256
	s_waitcnt vmcnt(14)
	v_lshlrev_b32_e32 v218, 16, v138
	v_and_b32_e32 v219, 0xffff0000, v138
	v_pk_mul_f32 v[116:117], v[116:117], v[218:219]
	v_lshlrev_b32_e32 v218, 16, v139
	v_and_b32_e32 v219, 0xffff0000, v139
	v_pk_mul_f32 v[118:119], v[118:119], v[218:219]
	v_lshlrev_b32_e32 v218, 16, v140
	v_and_b32_e32 v219, 0xffff0000, v140
	v_pk_mul_f32 v[112:113], v[112:113], v[218:219]
	v_lshlrev_b32_e32 v218, 16, v141
	v_and_b32_e32 v219, 0xffff0000, v141
	v_pk_mul_f32 v[114:115], v[114:115], v[218:219]
	v_lshlrev_b32_e32 v218, 16, v170
	v_and_b32_e32 v219, 0xffff0000, v170
	v_pk_add_f32 v[116:117], v[116:117], v[218:219]
	v_lshlrev_b32_e32 v218, 16, v171
	v_and_b32_e32 v219, 0xffff0000, v171
	v_pk_add_f32 v[118:119], v[118:119], v[218:219]
	v_lshlrev_b32_e32 v218, 16, v172
	v_and_b32_e32 v219, 0xffff0000, v172
	v_pk_add_f32 v[112:113], v[112:113], v[218:219]
	v_lshlrev_b32_e32 v218, 16, v173
	v_and_b32_e32 v219, 0xffff0000, v173
	v_pk_add_f32 v[114:115], v[114:115], v[218:219]
	v_cvt_pk_bf16_f32 v138, v116, v117
	v_cvt_pk_bf16_f32 v139, v118, v119
	v_cvt_pk_bf16_f32 v140, v112, v113
	v_cvt_pk_bf16_f32 v141, v114, v115
	global_store_dwordx4 v[212:213], v[138:141], off offset:256
	s_nop 0
	v_lshl_add_u64 v[212:213], v[212:213], 0, s[36:37]
	s_waitcnt vmcnt(13)
	v_lshlrev_b32_e32 v218, 16, v142
	v_and_b32_e32 v219, 0xffff0000, v142
	v_pk_mul_f32 v[100:101], v[100:101], v[218:219]
	v_lshlrev_b32_e32 v218, 16, v143
	v_and_b32_e32 v219, 0xffff0000, v143
	v_pk_mul_f32 v[102:103], v[102:103], v[218:219]
	v_lshlrev_b32_e32 v218, 16, v144
	v_and_b32_e32 v219, 0xffff0000, v144
	v_pk_mul_f32 v[96:97], v[96:97], v[218:219]
	v_lshlrev_b32_e32 v218, 16, v145
	v_and_b32_e32 v219, 0xffff0000, v145
	v_pk_mul_f32 v[98:99], v[98:99], v[218:219]
	v_lshlrev_b32_e32 v218, 16, v174
	v_and_b32_e32 v219, 0xffff0000, v174
	v_pk_add_f32 v[100:101], v[100:101], v[218:219]
	v_lshlrev_b32_e32 v218, 16, v175
	v_and_b32_e32 v219, 0xffff0000, v175
	v_pk_add_f32 v[102:103], v[102:103], v[218:219]
	v_lshlrev_b32_e32 v218, 16, v176
	v_and_b32_e32 v219, 0xffff0000, v176
	v_pk_add_f32 v[96:97], v[96:97], v[218:219]
	v_lshlrev_b32_e32 v218, 16, v177
	v_and_b32_e32 v219, 0xffff0000, v177
	v_pk_add_f32 v[98:99], v[98:99], v[218:219]
	v_cvt_pk_bf16_f32 v142, v100, v101
	v_cvt_pk_bf16_f32 v143, v102, v103
	v_cvt_pk_bf16_f32 v144, v96, v97
	v_cvt_pk_bf16_f32 v145, v98, v99
	global_store_dwordx4 v[212:213], v[142:145], off offset:256
	s_nop 0
	v_lshl_add_u64 v[212:213], v[212:213], 0, s[36:37]
	s_waitcnt vmcnt(12)
	v_lshlrev_b32_e32 v218, 16, v146
	v_and_b32_e32 v219, 0xffff0000, v146
	v_pk_mul_f32 v[84:85], v[84:85], v[218:219]
	v_lshlrev_b32_e32 v218, 16, v147
	v_and_b32_e32 v219, 0xffff0000, v147
	v_pk_mul_f32 v[86:87], v[86:87], v[218:219]
	v_lshlrev_b32_e32 v218, 16, v148
	v_and_b32_e32 v219, 0xffff0000, v148
	v_pk_mul_f32 v[80:81], v[80:81], v[218:219]
	v_lshlrev_b32_e32 v218, 16, v149
	v_and_b32_e32 v219, 0xffff0000, v149
	v_pk_mul_f32 v[82:83], v[82:83], v[218:219]
	v_lshlrev_b32_e32 v218, 16, v178
	v_and_b32_e32 v219, 0xffff0000, v178
	v_pk_add_f32 v[84:85], v[84:85], v[218:219]
	v_lshlrev_b32_e32 v218, 16, v179
	v_and_b32_e32 v219, 0xffff0000, v179
	v_pk_add_f32 v[86:87], v[86:87], v[218:219]
	v_lshlrev_b32_e32 v218, 16, v180
	v_and_b32_e32 v219, 0xffff0000, v180
	v_pk_add_f32 v[80:81], v[80:81], v[218:219]
	v_lshlrev_b32_e32 v218, 16, v181
	v_and_b32_e32 v219, 0xffff0000, v181
	v_pk_add_f32 v[82:83], v[82:83], v[218:219]
	v_cvt_pk_bf16_f32 v146, v84, v85
	v_cvt_pk_bf16_f32 v147, v86, v87
	v_cvt_pk_bf16_f32 v148, v80, v81
	v_cvt_pk_bf16_f32 v149, v82, v83
	global_store_dwordx4 v[212:213], v[146:149], off offset:256
	s_nop 0
	v_lshl_add_u64 v[212:213], v[212:213], 0, s[36:37]
	s_waitcnt vmcnt(11)
	v_lshlrev_b32_e32 v218, 16, v150
	v_and_b32_e32 v219, 0xffff0000, v150
	v_pk_mul_f32 v[68:69], v[68:69], v[218:219]
	v_lshlrev_b32_e32 v218, 16, v151
	v_and_b32_e32 v219, 0xffff0000, v151
	v_pk_mul_f32 v[70:71], v[70:71], v[218:219]
	v_lshlrev_b32_e32 v218, 16, v152
	v_and_b32_e32 v219, 0xffff0000, v152
	v_pk_mul_f32 v[64:65], v[64:65], v[218:219]
	v_lshlrev_b32_e32 v218, 16, v153
	v_and_b32_e32 v219, 0xffff0000, v153
	v_pk_mul_f32 v[66:67], v[66:67], v[218:219]
	v_lshlrev_b32_e32 v218, 16, v182
	v_and_b32_e32 v219, 0xffff0000, v182
	v_pk_add_f32 v[68:69], v[68:69], v[218:219]
	v_lshlrev_b32_e32 v218, 16, v183
	v_and_b32_e32 v219, 0xffff0000, v183
	v_pk_add_f32 v[70:71], v[70:71], v[218:219]
	v_lshlrev_b32_e32 v218, 16, v184
	v_and_b32_e32 v219, 0xffff0000, v184
	v_pk_add_f32 v[64:65], v[64:65], v[218:219]
	v_lshlrev_b32_e32 v218, 16, v185
	v_and_b32_e32 v219, 0xffff0000, v185
	v_pk_add_f32 v[66:67], v[66:67], v[218:219]
	v_cvt_pk_bf16_f32 v150, v68, v69
	v_cvt_pk_bf16_f32 v151, v70, v71
	v_cvt_pk_bf16_f32 v152, v64, v65
	v_cvt_pk_bf16_f32 v153, v66, v67
	global_store_dwordx4 v[212:213], v[150:153], off offset:256
	s_nop 0
	v_lshl_add_u64 v[212:213], v[212:213], 0, s[44:45]
	s_waitcnt vmcnt(10)
	v_lshlrev_b32_e32 v218, 16, v154
	v_and_b32_e32 v219, 0xffff0000, v154
	v_pk_mul_f32 v[52:53], v[52:53], v[218:219]
	v_lshlrev_b32_e32 v218, 16, v155
	v_and_b32_e32 v219, 0xffff0000, v155
	v_pk_mul_f32 v[54:55], v[54:55], v[218:219]
	v_lshlrev_b32_e32 v218, 16, v156
	v_and_b32_e32 v219, 0xffff0000, v156
	v_pk_mul_f32 v[48:49], v[48:49], v[218:219]
	v_lshlrev_b32_e32 v218, 16, v157
	v_and_b32_e32 v219, 0xffff0000, v157
	v_pk_mul_f32 v[50:51], v[50:51], v[218:219]
	v_lshlrev_b32_e32 v218, 16, v186
	v_and_b32_e32 v219, 0xffff0000, v186
	v_pk_add_f32 v[52:53], v[52:53], v[218:219]
	v_lshlrev_b32_e32 v218, 16, v187
	v_and_b32_e32 v219, 0xffff0000, v187
	v_pk_add_f32 v[54:55], v[54:55], v[218:219]
	v_lshlrev_b32_e32 v218, 16, v188
	v_and_b32_e32 v219, 0xffff0000, v188
	v_pk_add_f32 v[48:49], v[48:49], v[218:219]
	v_lshlrev_b32_e32 v218, 16, v189
	v_and_b32_e32 v219, 0xffff0000, v189
	v_pk_add_f32 v[50:51], v[50:51], v[218:219]
	v_cvt_pk_bf16_f32 v154, v52, v53
	v_cvt_pk_bf16_f32 v155, v54, v55
	v_cvt_pk_bf16_f32 v156, v48, v49
	v_cvt_pk_bf16_f32 v157, v50, v51
	global_store_dwordx4 v[212:213], v[154:157], off offset:256
	s_nop 0
	v_lshl_add_u64 v[212:213], v[212:213], 0, s[36:37]
	s_waitcnt vmcnt(9)
	v_lshlrev_b32_e32 v218, 16, v158
	v_and_b32_e32 v219, 0xffff0000, v158
	v_pk_mul_f32 v[36:37], v[36:37], v[218:219]
	v_lshlrev_b32_e32 v218, 16, v159
	v_and_b32_e32 v219, 0xffff0000, v159
	v_pk_mul_f32 v[38:39], v[38:39], v[218:219]
	v_lshlrev_b32_e32 v218, 16, v160
	v_and_b32_e32 v219, 0xffff0000, v160
	v_pk_mul_f32 v[32:33], v[32:33], v[218:219]
	v_lshlrev_b32_e32 v218, 16, v161
	v_and_b32_e32 v219, 0xffff0000, v161
	v_pk_mul_f32 v[34:35], v[34:35], v[218:219]
	v_lshlrev_b32_e32 v218, 16, v190
	v_and_b32_e32 v219, 0xffff0000, v190
	v_pk_add_f32 v[36:37], v[36:37], v[218:219]
	v_lshlrev_b32_e32 v218, 16, v191
	v_and_b32_e32 v219, 0xffff0000, v191
	v_pk_add_f32 v[38:39], v[38:39], v[218:219]
	v_lshlrev_b32_e32 v218, 16, v192
	v_and_b32_e32 v219, 0xffff0000, v192
	v_pk_add_f32 v[32:33], v[32:33], v[218:219]
	v_lshlrev_b32_e32 v218, 16, v193
	v_and_b32_e32 v219, 0xffff0000, v193
	v_pk_add_f32 v[34:35], v[34:35], v[218:219]
	v_cvt_pk_bf16_f32 v158, v36, v37
	v_cvt_pk_bf16_f32 v159, v38, v39
	v_cvt_pk_bf16_f32 v160, v32, v33
	v_cvt_pk_bf16_f32 v161, v34, v35
	global_store_dwordx4 v[212:213], v[158:161], off offset:256
	s_nop 0
	v_lshl_add_u64 v[212:213], v[212:213], 0, s[36:37]
	s_waitcnt vmcnt(8)
	v_lshlrev_b32_e32 v218, 16, v162
	v_and_b32_e32 v219, 0xffff0000, v162
	v_pk_mul_f32 v[20:21], v[20:21], v[218:219]
	v_lshlrev_b32_e32 v218, 16, v163
	v_and_b32_e32 v219, 0xffff0000, v163
	v_pk_mul_f32 v[22:23], v[22:23], v[218:219]
	v_lshlrev_b32_e32 v218, 16, v164
	v_and_b32_e32 v219, 0xffff0000, v164
	v_pk_mul_f32 v[16:17], v[16:17], v[218:219]
	v_lshlrev_b32_e32 v218, 16, v165
	v_and_b32_e32 v219, 0xffff0000, v165
	v_pk_mul_f32 v[18:19], v[18:19], v[218:219]
	v_lshlrev_b32_e32 v218, 16, v130
	v_and_b32_e32 v219, 0xffff0000, v130
	v_pk_add_f32 v[20:21], v[20:21], v[218:219]
	v_lshlrev_b32_e32 v218, 16, v131
	v_and_b32_e32 v219, 0xffff0000, v131
	v_pk_add_f32 v[22:23], v[22:23], v[218:219]
	v_lshlrev_b32_e32 v218, 16, v132
	v_and_b32_e32 v219, 0xffff0000, v132
	v_pk_add_f32 v[16:17], v[16:17], v[218:219]
	v_lshlrev_b32_e32 v218, 16, v133
	v_and_b32_e32 v219, 0xffff0000, v133
	v_pk_add_f32 v[18:19], v[18:19], v[218:219]
	v_cvt_pk_bf16_f32 v162, v20, v21
	v_cvt_pk_bf16_f32 v163, v22, v23
	v_cvt_pk_bf16_f32 v164, v16, v17
	v_cvt_pk_bf16_f32 v165, v18, v19
	global_store_dwordx4 v[212:213], v[162:165], off offset:256
	s_nop 0
	v_lshl_add_u64 v[212:213], v[212:213], 0, s[36:37]
	s_waitcnt vmcnt(7)
	v_lshlrev_b32_e32 v218, 16, v166
	v_and_b32_e32 v219, 0xffff0000, v166
	v_pk_mul_f32 v[4:5], v[4:5], v[218:219]
	v_lshlrev_b32_e32 v218, 16, v167
	v_and_b32_e32 v219, 0xffff0000, v167
	v_pk_mul_f32 v[6:7], v[6:7], v[218:219]
	v_lshlrev_b32_e32 v218, 16, v168
	v_and_b32_e32 v219, 0xffff0000, v168
	v_pk_mul_f32 v[0:1], v[0:1], v[218:219]
	v_lshlrev_b32_e32 v218, 16, v169
	v_and_b32_e32 v219, 0xffff0000, v169
	v_pk_mul_f32 v[2:3], v[2:3], v[218:219]
	v_lshlrev_b32_e32 v218, 16, v134
	v_and_b32_e32 v219, 0xffff0000, v134
	v_pk_add_f32 v[4:5], v[4:5], v[218:219]
	v_lshlrev_b32_e32 v218, 16, v135
	v_and_b32_e32 v219, 0xffff0000, v135
	v_pk_add_f32 v[6:7], v[6:7], v[218:219]
	v_lshlrev_b32_e32 v218, 16, v136
	v_and_b32_e32 v219, 0xffff0000, v136
	v_pk_add_f32 v[0:1], v[0:1], v[218:219]
	v_lshlrev_b32_e32 v218, 16, v137
	v_and_b32_e32 v219, 0xffff0000, v137
	v_pk_add_f32 v[2:3], v[2:3], v[218:219]
	v_cvt_pk_bf16_f32 v166, v4, v5
	v_cvt_pk_bf16_f32 v167, v6, v7
	v_cvt_pk_bf16_f32 v168, v0, v1
	v_cvt_pk_bf16_f32 v169, v2, v3
	global_store_dwordx4 v[212:213], v[166:169], off offset:256
	s_branch .LBB0_1411
